# P6: SCHED codes fetched at phase entry (hidden behind the conv); loop-head fetch only on re-entry
# speedup vs baseline: 1.0035x; 1.0018x over previous
.LBB0_547:
	s_cmp_lt_i32 s90, 7
	s_cselect_b64 s[2:3], -1, 0
	s_add_u32 s4, s94, 0x10400000
	s_addc_u32 s5, s95, 0
	s_and_b64 s[34:35], s[2:3], s[0:1]
	v_writelane_b32 v240, s4, 11
	s_andn2_b64 vcc, exec, s[34:35]
	s_nop 0
	v_writelane_b32 v240, s5, 12
	s_cbranch_vccnz .LBB0_624
	v_lshlrev_b32_e32 v243, 2, v147
	v_readlane_b32 s98, v241, 35
	v_readlane_b32 s99, v241, 36
	v_readlane_b32 s100, v241, 37
	v_readlane_b32 s101, v241, 38
	s_nop 4
	global_load_dword v244, v243, s[98:99]
	global_load_dword v245, v243, s[100:101]
	v_readlane_b32 s98, v241, 39
	v_readlane_b32 s99, v241, 40
	v_readlane_b32 s100, v241, 41
	v_readlane_b32 s101, v241, 42
	s_nop 4
	global_load_dword v246, v243, s[98:99]
	global_load_dword v247, v243, s[100:101]
	s_getpc_b64 s[98:99]
	s_add_u32 s98, s98, _ZL5SCHED@rel32@lo+4
	s_addc_u32 s99, s99, _ZL5SCHED@rel32@hi+12
	s_mul_i32 s100, s72, 6
	s_add_u32 s98, s98, s100
	s_addc_u32 s99, s99, 0
	v_lshlrev_b32_e32 v248, 1, v147
	s_mov_b64 s[100:101], exec
	s_mov_b64 exec, 7
	global_load_ushort v242, v248, s[98:99]
	s_mov_b64 exec, s[100:101]
	s_cmpk_lt_i32 s73, 0x100
	s_cbranch_scc1 .LBB0_550
	v_mbcnt_lo_u32_b32 v1, -1, 0
	v_mbcnt_hi_u32_b32 v196, -1, v1
	v_and_b32_e32 v1, 64, v196
	v_add_u32_e32 v1, 64, v1
	v_xor_b32_e32 v202, 1, v196
	v_xor_b32_e32 v201, 2, v196
	v_xor_b32_e32 v200, 4, v196
	v_xor_b32_e32 v199, 8, v196
	v_xor_b32_e32 v198, 16, v196
	v_xor_b32_e32 v197, 32, v196
	s_cbranch_execz .LBB0_551
	s_branch .LBB0_561

.LBB0_564:
	s_mul_hi_i32 s2, s0, 6
	v_writelane_b32 v240, s0, 34
	s_mul_i32 s3, s0, 6
	s_getpc_b64 s[0:1]
	s_add_u32 s0, s0, _ZL5SCHED@rel32@lo+4
	s_addc_u32 s1, s1, _ZL5SCHED@rel32@hi+12
	s_add_u32 s38, s0, s3
	s_addc_u32 s39, s1, s2
	v_readlane_b32 s98, v240, 4
	s_nop 3
	s_mul_i32 s98, s98, 6
	s_cmp_eq_u32 s3, s98
	s_cbranch_scc1 .Lp6_codes_ready
	v_lshlrev_b32_e32 v243, 1, v147
	s_mov_b64 s[98:99], exec
	s_mov_b64 exec, 7
	global_load_ushort v242, v243, s[38:39]
	s_mov_b64 exec, s[98:99]
.Lp6_codes_ready:
	s_waitcnt vmcnt(0)
	s_mov_b32 s20, s21
	s_branch .LBB0_567

	.amdhsa_kernel _Z10fwd_kernel4Args
		.amdhsa_group_segment_fixed_size 256
		.amdhsa_private_segment_fixed_size 0
		.amdhsa_kernarg_size 472
		.amdhsa_user_sgpr_count 2
		.amdhsa_user_sgpr_dispatch_ptr 0
		.amdhsa_user_sgpr_queue_ptr 0
		.amdhsa_user_sgpr_kernarg_segment_ptr 1
		.amdhsa_user_sgpr_dispatch_id 0
		.amdhsa_user_sgpr_kernarg_preload_length 0
		.amdhsa_user_sgpr_kernarg_preload_offset 0
		.amdhsa_user_sgpr_private_segment_size 0
		.amdhsa_uses_dynamic_stack 0
		.amdhsa_enable_private_segment 0
		.amdhsa_system_sgpr_workgroup_id_x 1
		.amdhsa_system_sgpr_workgroup_id_y 0
		.amdhsa_system_sgpr_workgroup_id_z 0
		.amdhsa_system_sgpr_workgroup_info 0
		.amdhsa_system_vgpr_workitem_id 2
		.amdhsa_next_free_vgpr 252
		.amdhsa_next_free_sgpr 102
		.amdhsa_accum_offset 252
		.amdhsa_reserve_vcc 1
		.amdhsa_float_round_mode_32 0
		.amdhsa_float_round_mode_16_64 0
		.amdhsa_float_denorm_mode_32 3
		.amdhsa_float_denorm_mode_16_64 3
		.amdhsa_dx10_clamp 1
		.amdhsa_ieee_mode 1
		.amdhsa_fp16_overflow 0
		.amdhsa_tg_split 0
		.amdhsa_exception_fp_ieee_invalid_op 0
		.amdhsa_exception_fp_denorm_src 0
		.amdhsa_exception_fp_ieee_div_zero 0
		.amdhsa_exception_fp_ieee_overflow 0
		.amdhsa_exception_fp_ieee_underflow 0
		.amdhsa_exception_fp_ieee_inexact 0
		.amdhsa_exception_int_div_zero 0
	.end_amdhsa_kernel

amdhsa.kernels:
  - .agpr_count:     0
    .args:
      - .offset:         0
        .size:           216
        .value_kind:     by_value
      - .offset:         216
        .size:           4
        .value_kind:     hidden_block_count_x
      - .offset:         220
        .size:           4
        .value_kind:     hidden_block_count_y
      - .offset:         224
        .size:           4
        .value_kind:     hidden_block_count_z
      - .offset:         228
        .size:           2
        .value_kind:     hidden_group_size_x
      - .offset:         230
        .size:           2
        .value_kind:     hidden_group_size_y
      - .offset:         232
        .size:           2
        .value_kind:     hidden_group_size_z
      - .offset:         234
        .size:           2
        .value_kind:     hidden_remainder_x
      - .offset:         236
        .size:           2
        .value_kind:     hidden_remainder_y
      - .offset:         238
        .size:           2
        .value_kind:     hidden_remainder_z
      - .offset:         256
        .size:           8
        .value_kind:     hidden_global_offset_x
      - .offset:         264
        .size:           8
        .value_kind:     hidden_global_offset_y
      - .offset:         272
        .size:           8
        .value_kind:     hidden_global_offset_z
      - .offset:         280
        .size:           2
        .value_kind:     hidden_grid_dims
      - .offset:         304
        .size:           8
        .value_kind:     hidden_multigrid_sync_arg
      - .offset:         336
        .size:           4
        .value_kind:     hidden_dynamic_lds_size
    .group_segment_fixed_size: 256
    .kernarg_segment_align: 8
    .kernarg_segment_size: 472
    .language:       OpenCL C
    .language_version:
      - 2
      - 0
    .max_flat_workgroup_size: 512
    .name:           _Z10fwd_kernel4Args
    .private_segment_fixed_size: 0
    .sgpr_count:     108
    .sgpr_spill_count: 103
    .symbol:         _Z10fwd_kernel4Args.kd
    .uniform_work_group_size: 1
    .uses_dynamic_stack: false
    .vgpr_count:     252
    .vgpr_spill_count: 0
    .wavefront_size: 64
